# waves 1..7 of every workgroup convert one weight item each while wave 0 runs the grid-barrier protocol after in-proj(l); attention-start converters take the rest
# speedup vs baseline: 1.0321x; 1.0045x over previous
.LBB0_244:
	s_or_b64 exec, exec, s[2:3]
	v_readlane_b32 s6, v255, 59
	s_cmp_lt_u32 s78, 3
	s_cbranch_scc0 .Lgb_skip
	s_and_b32 s7, s6, 7
	s_cmp_eq_u32 s7, 0
	s_cbranch_scc1 .Lgb_skip
	s_lshr_b32 s9, s6, 3
	s_mul_i32 s9, s9, 7
	s_add_u32 s9, s9, s7
	s_sub_u32 s6, s9, 1
	v_readlane_b32 s82, v255, 57
	v_readlane_b32 s83, v255, 58
	v_readlane_b32 s84, v255, 53
	v_readlane_b32 s85, v255, 54
	v_readlane_b32 s92, v255, 60
	v_readlane_b32 s93, v255, 61
	v_readlane_b32 s40, v255, 6
	v_readlane_b32 s41, v255, 7
	v_readlane_b32 s42, v255, 8
	v_readlane_b32 s43, v255, 9
	v_and_b32_e32 v12, 63, v243
	v_lshrrev_b32_e32 v6, 3, v12
	v_and_b32_e32 v7, 7, v12
	v_lshlrev_b32_e32 v8, 4, v7
	v_lshl_or_b32 v2, v6, 18, v8
	v_lshl_or_b32 v3, v6, 16, v8
	v_lshlrev_b32_e32 v11, 5, v6
	v_lshlrev_b32_e32 v9, 4, v6
	v_lshl_or_b32 v5, v7, 14, v9
	s_sub_u32 s47, 1, s78
	s_mul_i32 s47, s47, 0x2800
	s_add_u32 s7, s47, s6
	s_add_u32 s47, s6, 0x2000
	s_cmp_eq_u32 s78, 2
	s_cselect_b32 s7, s47, s7
	s_mul_hi_u32 s9, s7, 0x66666667
	s_lshr_b32 s9, s9, 12
	s_mul_i32 s10, s9, 0x2800
	s_sub_u32 s10, s7, s10
	s_sub_u32 s9, 3, s9
	s_cmp_lt_u32 s10, 0x2000
	s_cselect_b64 s[12:13], -1, 0
	s_cselect_b32 s11, 0, 0x2000
	s_cselect_b32 s14, 7, 5
	s_cselect_b32 s15, 15, 13
	s_cselect_b32 s48, 26, 24
	s_cselect_b32 s17, 25, 23
	s_cselect_b32 s20, s84, s92
	s_cselect_b32 s21, s85, s93
	s_cselect_b32 s22, s40, s42
	s_cselect_b32 s23, s41, s43
	s_sub_u32 s10, s10, s11
	s_lshr_b32 s24, s10, 3
	s_lshr_b32 s25, s24, s14
	s_lshl_b32 s26, s25, s14
	s_sub_u32 s24, s24, s26
	s_and_b32 s26, s10, 1
	s_lshl_b32 s24, s24, 1
	s_or_b32 s24, s24, s26
	s_bfe_u32 s26, s10, 0x20001
	s_lshl_b32 s25, s25, 2
	s_or_b32 s25, s25, s26
	s_lshl_b32 s25, s25, 6
	s_lshl_b32 s24, s24, 5
	s_lshl_b32 s26, s9, s48
	s_lshl_b32 s27, s25, s15
	s_add_u32 s26, s26, s27
	s_lshl_b32 s27, s24, 2
	s_add_u32 s26, s26, s27
	s_add_u32 s20, s20, s26
	s_addc_u32 s21, s21, 0
	s_lshl_b32 s28, 1, s15
	s_lshl_b32 s26, s9, s17
	s_lshl_b32 s27, s24, 12
	s_add_u32 s26, s26, s27
	s_lshl_b32 s27, s25, 1
	s_add_u32 s26, s26, s27
	s_add_u32 s22, s22, s26
	s_addc_u32 s23, s23, 0
	s_lshl_b32 s26, s9, 13
	s_lshl_b32 s27, s25, 2
	s_add_u32 s26, s26, s27
	s_add_u32 s30, s82, s26
	s_addc_u32 s31, s83, 0
	v_cndmask_b32_e64 v6, v3, v2, s[12:13]
	global_load_dwordx4 v[48:51], v11, s[30:31]
	global_load_dwordx4 v[52:55], v11, s[30:31] offset:16
	global_load_dwordx4 v[16:19], v6, s[20:21] nt
	s_add_u32 s20, s20, s28
	s_addc_u32 s21, s21, 0
	global_load_dwordx4 v[20:23], v6, s[20:21] nt
	s_add_u32 s20, s20, s28
	s_addc_u32 s21, s21, 0
	global_load_dwordx4 v[24:27], v6, s[20:21] nt
	s_add_u32 s20, s20, s28
	s_addc_u32 s21, s21, 0
	global_load_dwordx4 v[28:31], v6, s[20:21] nt
	s_add_u32 s20, s20, s28
	s_addc_u32 s21, s21, 0
	global_load_dwordx4 v[32:35], v6, s[20:21] nt
	s_add_u32 s20, s20, s28
	s_addc_u32 s21, s21, 0
	global_load_dwordx4 v[36:39], v6, s[20:21] nt
	s_add_u32 s20, s20, s28
	s_addc_u32 s21, s21, 0
	global_load_dwordx4 v[40:43], v6, s[20:21] nt
	s_add_u32 s20, s20, s28
	s_addc_u32 s21, s21, 0
	global_load_dwordx4 v[44:47], v6, s[20:21] nt
	s_waitcnt vmcnt(0)
	s_cmp_eq_u64 s[12:13], 0
	s_cbranch_scc1 .Lgb_nomul_g
	v_mul_f32_e32 v16, v16, v48
	v_mul_f32_e32 v17, v17, v48
	v_mul_f32_e32 v18, v18, v48
	v_mul_f32_e32 v19, v19, v48
	v_mul_f32_e32 v20, v20, v49
	v_mul_f32_e32 v21, v21, v49
	v_mul_f32_e32 v22, v22, v49
	v_mul_f32_e32 v23, v23, v49
	v_mul_f32_e32 v24, v24, v50
	v_mul_f32_e32 v25, v25, v50
	v_mul_f32_e32 v26, v26, v50
	v_mul_f32_e32 v27, v27, v50
	v_mul_f32_e32 v28, v28, v51
	v_mul_f32_e32 v29, v29, v51
	v_mul_f32_e32 v30, v30, v51
	v_mul_f32_e32 v31, v31, v51
	v_mul_f32_e32 v32, v32, v52
	v_mul_f32_e32 v33, v33, v52
	v_mul_f32_e32 v34, v34, v52
	v_mul_f32_e32 v35, v35, v52
	v_mul_f32_e32 v36, v36, v53
	v_mul_f32_e32 v37, v37, v53
	v_mul_f32_e32 v38, v38, v53
	v_mul_f32_e32 v39, v39, v53
	v_mul_f32_e32 v40, v40, v54
	v_mul_f32_e32 v41, v41, v54
	v_mul_f32_e32 v42, v42, v54
	v_mul_f32_e32 v43, v43, v54
	v_mul_f32_e32 v44, v44, v55
	v_mul_f32_e32 v45, v45, v55
	v_mul_f32_e32 v46, v46, v55
	v_mul_f32_e32 v47, v47, v55

.Lgb_skip:
	s_lshl_b32 s0, s78, 9
	s_mov_b32 s1, s63
	s_mov_b32 s2, s0
	v_writelane_b32 v255, s2, 45
	s_lshl_b64 s[0:1], s[0:1], 2
	s_add_u32 s86, s56, s0
	v_writelane_b32 v255, s3, 46
	s_addc_u32 s87, s57, s1
	v_readlane_b32 s2, v255, 14
	s_add_u32 s83, s2, s0
	v_readlane_b32 s0, v255, 15
	s_addc_u32 s82, s0, s1
	s_lshl_b32 s62, s78, 7
	v_readlane_b32 s0, v255, 26
	s_lshl_b64 s[84:85], s[62:63], 2
	v_readlane_b32 s6, v255, 32
	v_readlane_b32 s7, v255, 33
	s_add_u32 s88, s6, s84
	v_readlane_b32 s8, v255, 34
	s_addc_u32 s89, s7, s85
	v_readlane_b32 s1, v255, 27
	v_readlane_b32 s9, v255, 35
	s_add_u32 s90, s8, s84
	v_readlane_b32 s10, v255, 36
	s_addc_u32 s91, s9, s85
	s_mul_i32 s1, s78, 0x2800
	v_readlane_b32 s11, v255, 37
	s_mul_hi_u32 s0, s78, 0x2800
	s_add_u32 s92, s10, s1
	v_mov_b32_e32 v0, v243
	s_waitcnt lgkmcnt(0)
	s_barrier
	s_addc_u32 s93, s11, s0
	v_readlane_b32 s6, v255, 59
	s_cmp_lt_u32 s78, 3
	s_cbranch_scc0 .Lcv_skip
	s_cmp_lt_u32 s6, 0x400
	s_cbranch_scc0 .Lcv_skip
	s_add_u32 s6, s6, 0x700
	v_readlane_b32 s2, v255, 57
	v_readlane_b32 s3, v255, 58
	v_readlane_b32 s4, v255, 53
	v_readlane_b32 s5, v255, 54
	v_readlane_b32 s18, v255, 60
	v_readlane_b32 s19, v255, 61
	v_readlane_b32 s40, v255, 6
	v_readlane_b32 s41, v255, 7
	v_readlane_b32 s42, v255, 8
	v_readlane_b32 s43, v255, 9
	v_and_b32_e32 v12, 63, v243
	v_lshrrev_b32_e32 v6, 3, v12
	v_and_b32_e32 v7, 7, v12
	v_lshlrev_b32_e32 v8, 4, v7
	v_lshl_or_b32 v2, v6, 18, v8
	v_lshl_or_b32 v3, v6, 16, v8
	v_lshlrev_b32_e32 v11, 5, v6
	v_lshlrev_b32_e32 v9, 4, v6
	v_lshl_or_b32 v5, v7, 14, v9
	s_sub_u32 s47, 1, s78
	s_mul_i32 s47, s47, 0x2800
	s_add_u32 s7, s47, s6
	s_add_u32 s59, s47, 0x2000
	s_add_u32 s47, s6, 0x2000
	s_sub_u32 s58, 3, s78
	s_mul_i32 s58, s58, 0x2800
	s_cmp_eq_u32 s78, 2
	s_cselect_b32 s59, 0x80000000, s59
	s_cselect_b32 s7, s47, s7
	s_cmp_lt_u32 s7, s58
	s_cbranch_scc0 .Lcv_skip
	s_mul_hi_u32 s9, s7, 0x66666667
	s_lshr_b32 s9, s9, 12
	s_mul_i32 s10, s9, 0x2800
	s_sub_u32 s10, s7, s10
	s_sub_u32 s9, 3, s9
	s_cmp_lt_u32 s10, 0x2000
	s_cselect_b64 s[12:13], -1, 0
	s_cselect_b32 s11, 0, 0x2000
	s_cselect_b32 s14, 7, 5
	s_cselect_b32 s15, 15, 13
	s_cselect_b32 s48, 26, 24
	s_cselect_b32 s17, 25, 23
	s_cselect_b32 s20, s4, s18
	s_cselect_b32 s21, s5, s19
	s_cselect_b32 s22, s40, s42
	s_cselect_b32 s23, s41, s43
	s_sub_u32 s10, s10, s11
	s_lshr_b32 s24, s10, 3
	s_lshr_b32 s25, s24, s14
	s_lshl_b32 s26, s25, s14
	s_sub_u32 s24, s24, s26
	s_and_b32 s26, s10, 1
	s_lshl_b32 s24, s24, 1
	s_or_b32 s24, s24, s26
	s_bfe_u32 s26, s10, 0x20001
	s_lshl_b32 s25, s25, 2
	s_or_b32 s25, s25, s26
	s_lshl_b32 s25, s25, 6
	s_lshl_b32 s24, s24, 5
	s_lshl_b32 s26, s9, s48
	s_lshl_b32 s27, s25, s15
	s_add_u32 s26, s26, s27
	s_lshl_b32 s27, s24, 2
	s_add_u32 s26, s26, s27
	s_add_u32 s20, s20, s26
	s_addc_u32 s21, s21, 0
	s_lshl_b32 s28, 1, s15
	s_lshl_b32 s26, s9, s17
	s_lshl_b32 s27, s24, 12
	s_add_u32 s26, s26, s27
	s_lshl_b32 s27, s25, 1
	s_add_u32 s26, s26, s27
	s_add_u32 s22, s22, s26
	s_addc_u32 s23, s23, 0
	s_lshl_b32 s26, s9, 13
	s_lshl_b32 s27, s25, 2
	s_add_u32 s26, s26, s27
	s_add_u32 s30, s2, s26
	s_addc_u32 s31, s3, 0
	v_cndmask_b32_e64 v6, v3, v2, s[12:13]
	global_load_dwordx4 v[48:51], v11, s[30:31]
	global_load_dwordx4 v[52:55], v11, s[30:31] offset:16
	global_load_dwordx4 v[16:19], v6, s[20:21] nt
	s_add_u32 s20, s20, s28
	s_addc_u32 s21, s21, 0
	global_load_dwordx4 v[20:23], v6, s[20:21] nt
	s_add_u32 s20, s20, s28
	s_addc_u32 s21, s21, 0
	global_load_dwordx4 v[24:27], v6, s[20:21] nt
	s_add_u32 s20, s20, s28
	s_addc_u32 s21, s21, 0
	global_load_dwordx4 v[28:31], v6, s[20:21] nt
	s_add_u32 s20, s20, s28
	s_addc_u32 s21, s21, 0
	global_load_dwordx4 v[32:35], v6, s[20:21] nt
	s_add_u32 s20, s20, s28
	s_addc_u32 s21, s21, 0
	global_load_dwordx4 v[36:39], v6, s[20:21] nt
	s_add_u32 s20, s20, s28
	s_addc_u32 s21, s21, 0
	global_load_dwordx4 v[40:43], v6, s[20:21] nt
	s_add_u32 s20, s20, s28
	s_addc_u32 s21, s21, 0
	global_load_dwordx4 v[44:47], v6, s[20:21] nt
	s_add_u32 s46, s7, 0x400
	s_sub_u32 s47, s46, s59
	s_cmp_lt_u32 s47, 0x400
	s_cselect_b32 s47, 0x2800, 0
	s_add_u32 s46, s46, s47
	s_cmp_lt_u32 s46, s58
	s_cbranch_scc0 .Lcv_nob0
	s_mul_hi_u32 s9, s46, 0x66666667
	s_lshr_b32 s9, s9, 12
	s_mul_i32 s10, s9, 0x2800
	s_sub_u32 s10, s46, s10
	s_sub_u32 s9, 3, s9
	s_cmp_lt_u32 s10, 0x2000
	s_cselect_b64 s[50:51], -1, 0
	s_cselect_b32 s11, 0, 0x2000
	s_cselect_b32 s14, 7, 5
	s_cselect_b32 s15, 15, 13
	s_cselect_b32 s48, 26, 24
	s_cselect_b32 s17, 25, 23
	s_cselect_b32 s38, s4, s18
	s_cselect_b32 s39, s5, s19
	s_cselect_b32 s34, s40, s42
	s_cselect_b32 s35, s41, s43
	s_sub_u32 s10, s10, s11
	s_lshr_b32 s24, s10, 3
	s_lshr_b32 s25, s24, s14
	s_lshl_b32 s26, s25, s14
	s_sub_u32 s24, s24, s26
	s_and_b32 s26, s10, 1
	s_lshl_b32 s24, s24, 1
	s_or_b32 s24, s24, s26
	s_bfe_u32 s26, s10, 0x20001
	s_lshl_b32 s25, s25, 2
	s_or_b32 s25, s25, s26
	s_lshl_b32 s25, s25, 6
	s_lshl_b32 s24, s24, 5
	s_lshl_b32 s26, s9, s48
	s_lshl_b32 s27, s25, s15
	s_add_u32 s26, s26, s27
	s_lshl_b32 s27, s24, 2
	s_add_u32 s26, s26, s27
	s_add_u32 s38, s38, s26
	s_addc_u32 s39, s39, 0
	s_lshl_b32 s29, 1, s15
	s_lshl_b32 s26, s9, s17
	s_lshl_b32 s27, s24, 12
	s_add_u32 s26, s26, s27
	s_lshl_b32 s27, s25, 1
	s_add_u32 s26, s26, s27
	s_add_u32 s34, s34, s26
	s_addc_u32 s35, s35, 0
	s_lshl_b32 s26, s9, 13
	s_lshl_b32 s27, s25, 2
	s_add_u32 s26, s26, s27
	s_add_u32 s56, s2, s26
	s_addc_u32 s57, s3, 0
	v_cndmask_b32_e64 v7, v3, v2, s[50:51]
	global_load_dwordx4 v[96:99], v11, s[56:57]
	global_load_dwordx4 v[100:103], v11, s[56:57] offset:16
	global_load_dwordx4 v[64:67], v7, s[38:39] nt
	s_add_u32 s38, s38, s29
	s_addc_u32 s39, s39, 0
	global_load_dwordx4 v[68:71], v7, s[38:39] nt
	s_add_u32 s38, s38, s29
	s_addc_u32 s39, s39, 0
	global_load_dwordx4 v[72:75], v7, s[38:39] nt
	s_add_u32 s38, s38, s29
	s_addc_u32 s39, s39, 0
	global_load_dwordx4 v[76:79], v7, s[38:39] nt
	s_add_u32 s38, s38, s29
	s_addc_u32 s39, s39, 0
	global_load_dwordx4 v[80:83], v7, s[38:39] nt
	s_add_u32 s38, s38, s29
	s_addc_u32 s39, s39, 0
	global_load_dwordx4 v[84:87], v7, s[38:39] nt
	s_add_u32 s38, s38, s29
	s_addc_u32 s39, s39, 0
	global_load_dwordx4 v[88:91], v7, s[38:39] nt
	s_add_u32 s38, s38, s29
	s_addc_u32 s39, s39, 0
	global_load_dwordx4 v[92:95], v7, s[38:39] nt
	s_waitcnt vmcnt(10)
	s_branch .Lcv_loop
